# gain-path weight transposes: all 4 row steps of a tile in one batch (64 loads in flight, counted waits) instead of 8 per round trip
# baseline (speedup 1.0000x reference)
; __device__ __forceinline__ void transpose_item(const float* W, const float* gain, int K, int N, bf16_t* WT, int mode, LAS float* scr, int item, int lane) {
;     ...
; #pragma unroll 8
;     for (int i = 0; i < 32; ++i) { const int kk = 2 * i + (lane >> 5); const float g = gain ? gain[k0 + kk] : 1.0f; scr[kk * 33 + (lane & 31)] = W[(size_t)(k0 + kk) * N + n0 + (lane & 31)] * g; }
.LBB0_618:
	s_andn2_b64 vcc, exec, s[20:21]
	s_cbranch_vccnz .Ltga_nogain
	v_lshl_add_u64 v[112:113], s[22:23], 0, v[0:1]
	v_lshl_add_u64 v[114:115], s[22:23], 0, v[18:19]
	global_load_dword v120, v[112:113], off
	global_load_dword v121, v[114:115], off offset:8
	global_load_dword v122, v[114:115], off offset:16
	global_load_dword v123, v[114:115], off offset:24
	global_load_dword v124, v[114:115], off offset:32
	global_load_dword v125, v[114:115], off offset:40
	global_load_dword v126, v[114:115], off offset:48
	global_load_dword v127, v[114:115], off offset:56
	global_load_dword v128, v[112:113], off offset:64
	global_load_dword v129, v[114:115], off offset:72
	global_load_dword v130, v[114:115], off offset:80
	global_load_dword v131, v[114:115], off offset:88
	global_load_dword v132, v[114:115], off offset:96
	global_load_dword v133, v[114:115], off offset:104
	global_load_dword v134, v[114:115], off offset:112
	global_load_dword v135, v[114:115], off offset:120
	global_load_dword v136, v[112:113], off offset:128
	global_load_dword v137, v[114:115], off offset:136
	global_load_dword v138, v[114:115], off offset:144
	global_load_dword v139, v[114:115], off offset:152
	global_load_dword v140, v[114:115], off offset:160
	global_load_dword v141, v[114:115], off offset:168
	global_load_dword v142, v[114:115], off offset:176
	global_load_dword v143, v[114:115], off offset:184
	global_load_dword v144, v[112:113], off offset:192
	global_load_dword v145, v[114:115], off offset:200
	global_load_dword v146, v[114:115], off offset:208
	global_load_dword v147, v[114:115], off offset:216
	global_load_dword v148, v[114:115], off offset:224
	global_load_dword v149, v[114:115], off offset:232
	global_load_dword v150, v[114:115], off offset:240
	global_load_dword v151, v[114:115], off offset:248
	s_branch .Ltga_w
.Ltga_nogain:
	v_mov_b32_e32 v120, 1.0
	v_mov_b32_e32 v121, 1.0
	v_mov_b32_e32 v122, 1.0
	v_mov_b32_e32 v123, 1.0
	v_mov_b32_e32 v124, 1.0
	v_mov_b32_e32 v125, 1.0
	v_mov_b32_e32 v126, 1.0
	v_mov_b32_e32 v127, 1.0
	v_mov_b32_e32 v128, 1.0
	v_mov_b32_e32 v129, 1.0
	v_mov_b32_e32 v130, 1.0
	v_mov_b32_e32 v131, 1.0
	v_mov_b32_e32 v132, 1.0
	v_mov_b32_e32 v133, 1.0
	v_mov_b32_e32 v134, 1.0
	v_mov_b32_e32 v135, 1.0
	v_mov_b32_e32 v136, 1.0
	v_mov_b32_e32 v137, 1.0
	v_mov_b32_e32 v138, 1.0
	v_mov_b32_e32 v139, 1.0
	v_mov_b32_e32 v140, 1.0
	v_mov_b32_e32 v141, 1.0
	v_mov_b32_e32 v142, 1.0
	v_mov_b32_e32 v143, 1.0
	v_mov_b32_e32 v144, 1.0
	v_mov_b32_e32 v145, 1.0
	v_mov_b32_e32 v146, 1.0
	v_mov_b32_e32 v147, 1.0
	v_mov_b32_e32 v148, 1.0
	v_mov_b32_e32 v149, 1.0
	v_mov_b32_e32 v150, 1.0
	v_mov_b32_e32 v151, 1.0
; __device__ __forceinline__ void transpose_item(const float* W, const float* gain, int K, int N, bf16_t* WT, int mode, LAS float* scr, int item, int lane) {
;     ...
;     for (int i = 0; i < 32; ++i) { const int kk = 2 * i + (lane >> 5); const float g = gain ? gain[k0 + kk] : 1.0f; scr[kk * 33 + (lane & 31)] = W[(size_t)(k0 + kk) * N + n0 + (lane & 31)] * g; }
.Ltga_w:
	v_lshl_add_u64 v[96:97], v[32:33], 0, s[8:9]
	global_load_dword v152, v[96:97], off
	v_lshl_add_u64 v[98:99], v[30:31], 0, s[8:9]
	global_load_dword v153, v[98:99], off
	v_lshl_add_u64 v[100:101], v[28:29], 0, s[8:9]
	global_load_dword v154, v[100:101], off
	v_lshl_add_u64 v[102:103], v[26:27], 0, s[8:9]
	global_load_dword v155, v[102:103], off
	v_lshl_add_u64 v[104:105], v[24:25], 0, s[8:9]
	global_load_dword v156, v[104:105], off
	v_lshl_add_u64 v[106:107], v[22:23], 0, s[8:9]
	global_load_dword v157, v[106:107], off
	v_lshl_add_u64 v[108:109], v[20:21], 0, s[8:9]
	global_load_dword v158, v[108:109], off
	v_lshl_add_u64 v[110:111], v[16:17], 0, s[8:9]
	global_load_dword v159, v[110:111], off
	s_add_u32 s8, s8, 0x2c000
	s_addc_u32 s9, s9, 0
	v_lshl_add_u64 v[184:185], v[32:33], 0, s[8:9]
	global_load_dword v160, v[184:185], off
	v_lshl_add_u64 v[186:187], v[30:31], 0, s[8:9]
	global_load_dword v161, v[186:187], off
	v_lshl_add_u64 v[188:189], v[28:29], 0, s[8:9]
	global_load_dword v162, v[188:189], off
	v_lshl_add_u64 v[190:191], v[26:27], 0, s[8:9]
	global_load_dword v163, v[190:191], off
	v_lshl_add_u64 v[192:193], v[24:25], 0, s[8:9]
	global_load_dword v164, v[192:193], off
	v_lshl_add_u64 v[194:195], v[22:23], 0, s[8:9]
	global_load_dword v165, v[194:195], off
	v_lshl_add_u64 v[196:197], v[20:21], 0, s[8:9]
	global_load_dword v166, v[196:197], off
	v_lshl_add_u64 v[198:199], v[16:17], 0, s[8:9]
	global_load_dword v167, v[198:199], off
	s_add_u32 s8, s8, 0x2c000
	s_addc_u32 s9, s9, 0
	v_lshl_add_u64 v[96:97], v[32:33], 0, s[8:9]
	global_load_dword v168, v[96:97], off
	v_lshl_add_u64 v[98:99], v[30:31], 0, s[8:9]
	global_load_dword v169, v[98:99], off
	v_lshl_add_u64 v[100:101], v[28:29], 0, s[8:9]
	global_load_dword v170, v[100:101], off
	v_lshl_add_u64 v[102:103], v[26:27], 0, s[8:9]
	global_load_dword v171, v[102:103], off
	v_lshl_add_u64 v[104:105], v[24:25], 0, s[8:9]
	global_load_dword v172, v[104:105], off
	v_lshl_add_u64 v[106:107], v[22:23], 0, s[8:9]
	global_load_dword v173, v[106:107], off
	v_lshl_add_u64 v[108:109], v[20:21], 0, s[8:9]
	global_load_dword v174, v[108:109], off
	v_lshl_add_u64 v[110:111], v[16:17], 0, s[8:9]
	global_load_dword v175, v[110:111], off
	s_add_u32 s8, s8, 0x2c000
	s_addc_u32 s9, s9, 0
	s_waitcnt vmcnt(30)
	v_lshl_add_u64 v[184:185], v[32:33], 0, s[8:9]
	global_load_dword v176, v[184:185], off
	v_lshl_add_u64 v[186:187], v[30:31], 0, s[8:9]
	global_load_dword v177, v[186:187], off
	v_lshl_add_u64 v[188:189], v[28:29], 0, s[8:9]
	global_load_dword v178, v[188:189], off
	v_lshl_add_u64 v[190:191], v[26:27], 0, s[8:9]
	global_load_dword v179, v[190:191], off
	v_lshl_add_u64 v[192:193], v[24:25], 0, s[8:9]
	global_load_dword v180, v[192:193], off
	v_lshl_add_u64 v[194:195], v[22:23], 0, s[8:9]
	global_load_dword v181, v[194:195], off
	v_lshl_add_u64 v[196:197], v[20:21], 0, s[8:9]
	global_load_dword v182, v[196:197], off
	v_lshl_add_u64 v[198:199], v[16:17], 0, s[8:9]
	global_load_dword v183, v[198:199], off
	s_add_u32 s8, s8, 0x2c000
	s_addc_u32 s9, s9, 0
	s_waitcnt vmcnt(24)
	v_mul_f32_e32 v152, v120, v152
	v_mul_f32_e32 v153, v121, v153
	v_mul_f32_e32 v154, v122, v154
	v_mul_f32_e32 v155, v123, v155
	v_mul_f32_e32 v156, v124, v156
	v_mul_f32_e32 v157, v125, v157
	v_mul_f32_e32 v158, v126, v158
	v_mul_f32_e32 v159, v127, v159
	ds_write_b32 v7, v152
	ds_write_b32 v7, v153 offset:264
	ds_write_b32 v7, v154 offset:528
	ds_write_b32 v7, v155 offset:792
	ds_write_b32 v7, v156 offset:1056
	ds_write_b32 v7, v157 offset:1320
	ds_write_b32 v7, v158 offset:1584
	ds_write_b32 v7, v159 offset:1848
	s_waitcnt vmcnt(16)
	v_mul_f32_e32 v160, v128, v160
	v_mul_f32_e32 v161, v129, v161
	v_mul_f32_e32 v162, v130, v162
	v_mul_f32_e32 v163, v131, v163
	v_mul_f32_e32 v164, v132, v164
	v_mul_f32_e32 v165, v133, v165
	v_mul_f32_e32 v166, v134, v166
	v_mul_f32_e32 v167, v135, v167
	ds_write_b32 v7, v160 offset:2112
	ds_write_b32 v7, v161 offset:2376
	ds_write_b32 v7, v162 offset:2640
	ds_write_b32 v7, v163 offset:2904
	ds_write_b32 v7, v164 offset:3168
	ds_write_b32 v7, v165 offset:3432
	ds_write_b32 v7, v166 offset:3696
	ds_write_b32 v7, v167 offset:3960
	s_waitcnt vmcnt(8)
	v_mul_f32_e32 v168, v136, v168
	v_mul_f32_e32 v169, v137, v169
	v_mul_f32_e32 v170, v138, v170
	v_mul_f32_e32 v171, v139, v171
	v_mul_f32_e32 v172, v140, v172
	v_mul_f32_e32 v173, v141, v173
	v_mul_f32_e32 v174, v142, v174
	v_mul_f32_e32 v175, v143, v175
	ds_write_b32 v7, v168 offset:4224
	ds_write_b32 v7, v169 offset:4488
	ds_write_b32 v7, v170 offset:4752
	ds_write_b32 v7, v171 offset:5016
	ds_write_b32 v7, v172 offset:5280
	ds_write_b32 v7, v173 offset:5544
	ds_write_b32 v7, v174 offset:5808
	ds_write_b32 v7, v175 offset:6072
	s_waitcnt vmcnt(0)
	v_mul_f32_e32 v176, v144, v176
	v_mul_f32_e32 v177, v145, v177
	v_mul_f32_e32 v178, v146, v178
	v_mul_f32_e32 v179, v147, v179
	v_mul_f32_e32 v180, v148, v180
	v_mul_f32_e32 v181, v149, v181
	v_mul_f32_e32 v182, v150, v182
	v_mul_f32_e32 v183, v151, v183
	ds_write_b32 v7, v176 offset:6336
	ds_write_b32 v7, v177 offset:6600
	ds_write_b32 v7, v178 offset:6864
	ds_write_b32 v7, v179 offset:7128
	ds_write_b32 v7, v180 offset:7392
	ds_write_b32 v7, v181 offset:7656
	ds_write_b32 v7, v182 offset:7920
	ds_write_b32 v7, v183 offset:8184
	s_add_u32 s22, s22, 0x100
	s_addc_u32 s23, s23, 0
	v_add_u32_e32 v7, 0x2100, v7

; __device__ __forceinline__ void transpose_item(const float* W, const float* gain, int K, int N, bf16_t* WT, int mode, LAS float* scr, int item, int lane) {
;     ...
;     for (int i = 0; i < 32; ++i) { const int kk = 2 * i + (lane >> 5); const float g = gain ? gain[k0 + kk] : 1.0f; scr[kk * 33 + (lane & 31)] = W[(size_t)(k0 + kk) * N + n0 + (lane & 31)] * g; }
.LBB0_639:
	s_andn2_b64 vcc, exec, s[20:21]
	s_cbranch_vccnz .Ltgb_nogain
	v_lshl_add_u64 v[112:113], s[0:1], 0, v[0:1]
	v_lshl_add_u64 v[114:115], s[0:1], 0, v[18:19]
	global_load_dword v120, v[112:113], off
	global_load_dword v121, v[114:115], off offset:8
	global_load_dword v122, v[114:115], off offset:16
	global_load_dword v123, v[114:115], off offset:24
	global_load_dword v124, v[114:115], off offset:32
	global_load_dword v125, v[114:115], off offset:40
	global_load_dword v126, v[114:115], off offset:48
	global_load_dword v127, v[114:115], off offset:56
	global_load_dword v128, v[112:113], off offset:64
	global_load_dword v129, v[114:115], off offset:72
	global_load_dword v130, v[114:115], off offset:80
	global_load_dword v131, v[114:115], off offset:88
	global_load_dword v132, v[114:115], off offset:96
	global_load_dword v133, v[114:115], off offset:104
	global_load_dword v134, v[114:115], off offset:112
	global_load_dword v135, v[114:115], off offset:120
	global_load_dword v136, v[112:113], off offset:128
	global_load_dword v137, v[114:115], off offset:136
	global_load_dword v138, v[114:115], off offset:144
	global_load_dword v139, v[114:115], off offset:152
	global_load_dword v140, v[114:115], off offset:160
	global_load_dword v141, v[114:115], off offset:168
	global_load_dword v142, v[114:115], off offset:176
	global_load_dword v143, v[114:115], off offset:184
	global_load_dword v144, v[112:113], off offset:192
	global_load_dword v145, v[114:115], off offset:200
	global_load_dword v146, v[114:115], off offset:208
	global_load_dword v147, v[114:115], off offset:216
	global_load_dword v148, v[114:115], off offset:224
	global_load_dword v149, v[114:115], off offset:232
	global_load_dword v150, v[114:115], off offset:240
	global_load_dword v151, v[114:115], off offset:248
	s_branch .Ltgb_w

; __device__ __forceinline__ void transpose_item(const float* W, const float* gain, int K, int N, bf16_t* WT, int mode, LAS float* scr, int item, int lane) {
;     ...
;     for (int i = 0; i < 32; ++i) { const int kk = 2 * i + (lane >> 5); const float g = gain ? gain[k0 + kk] : 1.0f; scr[kk * 33 + (lane & 31)] = W[(size_t)(k0 + kk) * N + n0 + (lane & 31)] * g; }
.Ltgb_w:
	v_lshl_add_u64 v[96:97], v[32:33], 0, s[8:9]
	global_load_dword v152, v[96:97], off
	v_lshl_add_u64 v[98:99], v[30:31], 0, s[8:9]
	global_load_dword v153, v[98:99], off
	v_lshl_add_u64 v[100:101], v[28:29], 0, s[8:9]
	global_load_dword v154, v[100:101], off
	v_lshl_add_u64 v[102:103], v[26:27], 0, s[8:9]
	global_load_dword v155, v[102:103], off
	v_lshl_add_u64 v[104:105], v[24:25], 0, s[8:9]
	global_load_dword v156, v[104:105], off
	v_lshl_add_u64 v[106:107], v[22:23], 0, s[8:9]
	global_load_dword v157, v[106:107], off
	v_lshl_add_u64 v[108:109], v[20:21], 0, s[8:9]
	global_load_dword v158, v[108:109], off
	v_lshl_add_u64 v[110:111], v[16:17], 0, s[8:9]
	global_load_dword v159, v[110:111], off
	s_add_u32 s8, s8, 0x2c000
	s_addc_u32 s9, s9, 0
	v_lshl_add_u64 v[184:185], v[32:33], 0, s[8:9]
	global_load_dword v160, v[184:185], off
	v_lshl_add_u64 v[186:187], v[30:31], 0, s[8:9]
	global_load_dword v161, v[186:187], off
	v_lshl_add_u64 v[188:189], v[28:29], 0, s[8:9]
	global_load_dword v162, v[188:189], off
	v_lshl_add_u64 v[190:191], v[26:27], 0, s[8:9]
	global_load_dword v163, v[190:191], off
	v_lshl_add_u64 v[192:193], v[24:25], 0, s[8:9]
	global_load_dword v164, v[192:193], off
	v_lshl_add_u64 v[194:195], v[22:23], 0, s[8:9]
	global_load_dword v165, v[194:195], off
	v_lshl_add_u64 v[196:197], v[20:21], 0, s[8:9]
	global_load_dword v166, v[196:197], off
	v_lshl_add_u64 v[198:199], v[16:17], 0, s[8:9]
	global_load_dword v167, v[198:199], off
	s_add_u32 s8, s8, 0x2c000
	s_addc_u32 s9, s9, 0
	v_lshl_add_u64 v[96:97], v[32:33], 0, s[8:9]
	global_load_dword v168, v[96:97], off
	v_lshl_add_u64 v[98:99], v[30:31], 0, s[8:9]
	global_load_dword v169, v[98:99], off
	v_lshl_add_u64 v[100:101], v[28:29], 0, s[8:9]
	global_load_dword v170, v[100:101], off
	v_lshl_add_u64 v[102:103], v[26:27], 0, s[8:9]
	global_load_dword v171, v[102:103], off
	v_lshl_add_u64 v[104:105], v[24:25], 0, s[8:9]
	global_load_dword v172, v[104:105], off
	v_lshl_add_u64 v[106:107], v[22:23], 0, s[8:9]
	global_load_dword v173, v[106:107], off
	v_lshl_add_u64 v[108:109], v[20:21], 0, s[8:9]
	global_load_dword v174, v[108:109], off
	v_lshl_add_u64 v[110:111], v[16:17], 0, s[8:9]
	global_load_dword v175, v[110:111], off
	s_add_u32 s8, s8, 0x2c000
	s_addc_u32 s9, s9, 0
	s_waitcnt vmcnt(30)
	v_lshl_add_u64 v[184:185], v[32:33], 0, s[8:9]
	global_load_dword v176, v[184:185], off
	v_lshl_add_u64 v[186:187], v[30:31], 0, s[8:9]
	global_load_dword v177, v[186:187], off
	v_lshl_add_u64 v[188:189], v[28:29], 0, s[8:9]
	global_load_dword v178, v[188:189], off
	v_lshl_add_u64 v[190:191], v[26:27], 0, s[8:9]
	global_load_dword v179, v[190:191], off
	v_lshl_add_u64 v[192:193], v[24:25], 0, s[8:9]
	global_load_dword v180, v[192:193], off
	v_lshl_add_u64 v[194:195], v[22:23], 0, s[8:9]
	global_load_dword v181, v[194:195], off
	v_lshl_add_u64 v[196:197], v[20:21], 0, s[8:9]
	global_load_dword v182, v[196:197], off
	v_lshl_add_u64 v[198:199], v[16:17], 0, s[8:9]
	global_load_dword v183, v[198:199], off
	s_add_u32 s8, s8, 0x2c000
	s_addc_u32 s9, s9, 0
	s_waitcnt vmcnt(24)
	v_mul_f32_e32 v152, v120, v152
	v_mul_f32_e32 v153, v121, v153
	v_mul_f32_e32 v154, v122, v154
	v_mul_f32_e32 v155, v123, v155
	v_mul_f32_e32 v156, v124, v156
	v_mul_f32_e32 v157, v125, v157
	v_mul_f32_e32 v158, v126, v158
	v_mul_f32_e32 v159, v127, v159
	ds_write_b32 v7, v152
	ds_write_b32 v7, v153 offset:264
	ds_write_b32 v7, v154 offset:528
	ds_write_b32 v7, v155 offset:792
	ds_write_b32 v7, v156 offset:1056
	ds_write_b32 v7, v157 offset:1320
	ds_write_b32 v7, v158 offset:1584
	ds_write_b32 v7, v159 offset:1848
	s_waitcnt vmcnt(16)
	v_mul_f32_e32 v160, v128, v160
	v_mul_f32_e32 v161, v129, v161
	v_mul_f32_e32 v162, v130, v162
	v_mul_f32_e32 v163, v131, v163
	v_mul_f32_e32 v164, v132, v164
	v_mul_f32_e32 v165, v133, v165
	v_mul_f32_e32 v166, v134, v166
	v_mul_f32_e32 v167, v135, v167
	ds_write_b32 v7, v160 offset:2112
	ds_write_b32 v7, v161 offset:2376
	ds_write_b32 v7, v162 offset:2640
	ds_write_b32 v7, v163 offset:2904
	ds_write_b32 v7, v164 offset:3168
	ds_write_b32 v7, v165 offset:3432
	ds_write_b32 v7, v166 offset:3696
	ds_write_b32 v7, v167 offset:3960
	s_waitcnt vmcnt(8)
	v_mul_f32_e32 v168, v136, v168
	v_mul_f32_e32 v169, v137, v169
	v_mul_f32_e32 v170, v138, v170
	v_mul_f32_e32 v171, v139, v171
	v_mul_f32_e32 v172, v140, v172
	v_mul_f32_e32 v173, v141, v173
	v_mul_f32_e32 v174, v142, v174
	v_mul_f32_e32 v175, v143, v175
	ds_write_b32 v7, v168 offset:4224
	ds_write_b32 v7, v169 offset:4488
	ds_write_b32 v7, v170 offset:4752
	ds_write_b32 v7, v171 offset:5016
	ds_write_b32 v7, v172 offset:5280
	ds_write_b32 v7, v173 offset:5544
	ds_write_b32 v7, v174 offset:5808
	ds_write_b32 v7, v175 offset:6072
	s_waitcnt vmcnt(0)
	v_mul_f32_e32 v176, v144, v176
	v_mul_f32_e32 v177, v145, v177
	v_mul_f32_e32 v178, v146, v178
	v_mul_f32_e32 v179, v147, v179
	v_mul_f32_e32 v180, v148, v180
	v_mul_f32_e32 v181, v149, v181
	v_mul_f32_e32 v182, v150, v182
	v_mul_f32_e32 v183, v151, v183
	ds_write_b32 v7, v176 offset:6336
	ds_write_b32 v7, v177 offset:6600
	ds_write_b32 v7, v178 offset:6864
	ds_write_b32 v7, v179 offset:7128
	ds_write_b32 v7, v180 offset:7392
	ds_write_b32 v7, v181 offset:7656
	ds_write_b32 v7, v182 offset:7920
	ds_write_b32 v7, v183 offset:8184
	s_add_u32 s0, s0, 0x100
	s_addc_u32 s1, s1, 0
	v_add_u32_e32 v7, 0x2100, v7

; __device__ __forceinline__ void transpose_item(const float* W, const float* gain, int K, int N, bf16_t* WT, int mode, LAS float* scr, int item, int lane) {
;     ...
;     for (int i = 0; i < 32; ++i) { const int kk = 2 * i + (lane >> 5); const float g = gain ? gain[k0 + kk] : 1.0f; scr[kk * 33 + (lane & 31)] = W[(size_t)(k0 + kk) * N + n0 + (lane & 31)] * g; }
.LBB0_664:
	s_andn2_b64 vcc, exec, s[22:23]
	s_cbranch_vccnz .Ltgc_nogain
	v_lshl_add_u64 v[112:113], s[8:9], 0, v[34:35]
	v_lshl_add_u64 v[114:115], s[8:9], 0, v[18:19]
	global_load_dword v120, v[112:113], off
	global_load_dword v121, v[114:115], off offset:8
	global_load_dword v122, v[114:115], off offset:16
	global_load_dword v123, v[114:115], off offset:24
	global_load_dword v124, v[114:115], off offset:32
	global_load_dword v125, v[114:115], off offset:40
	global_load_dword v126, v[114:115], off offset:48
	global_load_dword v127, v[114:115], off offset:56
	global_load_dword v128, v[112:113], off offset:64
	global_load_dword v129, v[114:115], off offset:72
	global_load_dword v130, v[114:115], off offset:80
	global_load_dword v131, v[114:115], off offset:88
	global_load_dword v132, v[114:115], off offset:96
	global_load_dword v133, v[114:115], off offset:104
	global_load_dword v134, v[114:115], off offset:112
	global_load_dword v135, v[114:115], off offset:120
	global_load_dword v136, v[112:113], off offset:128
	global_load_dword v137, v[114:115], off offset:136
	global_load_dword v138, v[114:115], off offset:144
	global_load_dword v139, v[114:115], off offset:152
	global_load_dword v140, v[114:115], off offset:160
	global_load_dword v141, v[114:115], off offset:168
	global_load_dword v142, v[114:115], off offset:176
	global_load_dword v143, v[114:115], off offset:184
	global_load_dword v144, v[112:113], off offset:192
	global_load_dword v145, v[114:115], off offset:200
	global_load_dword v146, v[114:115], off offset:208
	global_load_dword v147, v[114:115], off offset:216
	global_load_dword v148, v[114:115], off offset:224
	global_load_dword v149, v[114:115], off offset:232
	global_load_dword v150, v[114:115], off offset:240
	global_load_dword v151, v[114:115], off offset:248
	s_branch .Ltgc_w

; __device__ __forceinline__ void transpose_item(const float* W, const float* gain, int K, int N, bf16_t* WT, int mode, LAS float* scr, int item, int lane) {
;     ...
;     for (int i = 0; i < 32; ++i) { const int kk = 2 * i + (lane >> 5); const float g = gain ? gain[k0 + kk] : 1.0f; scr[kk * 33 + (lane & 31)] = W[(size_t)(k0 + kk) * N + n0 + (lane & 31)] * g; }
.Ltgc_w:
	v_lshl_add_u64 v[96:97], v[32:33], 0, s[20:21]
	global_load_dword v152, v[96:97], off
	v_lshl_add_u64 v[98:99], v[30:31], 0, s[20:21]
	global_load_dword v153, v[98:99], off
	v_lshl_add_u64 v[100:101], v[28:29], 0, s[20:21]
	global_load_dword v154, v[100:101], off
	v_lshl_add_u64 v[102:103], v[26:27], 0, s[20:21]
	global_load_dword v155, v[102:103], off
	v_lshl_add_u64 v[104:105], v[24:25], 0, s[20:21]
	global_load_dword v156, v[104:105], off
	v_lshl_add_u64 v[106:107], v[22:23], 0, s[20:21]
	global_load_dword v157, v[106:107], off
	v_lshl_add_u64 v[108:109], v[20:21], 0, s[20:21]
	global_load_dword v158, v[108:109], off
	v_lshl_add_u64 v[110:111], v[16:17], 0, s[20:21]
	global_load_dword v159, v[110:111], off
	s_add_u32 s20, s20, 0x30000
	s_addc_u32 s21, s21, 0
	v_lshl_add_u64 v[184:185], v[32:33], 0, s[20:21]
	global_load_dword v160, v[184:185], off
	v_lshl_add_u64 v[186:187], v[30:31], 0, s[20:21]
	global_load_dword v161, v[186:187], off
	v_lshl_add_u64 v[188:189], v[28:29], 0, s[20:21]
	global_load_dword v162, v[188:189], off
	v_lshl_add_u64 v[190:191], v[26:27], 0, s[20:21]
	global_load_dword v163, v[190:191], off
	v_lshl_add_u64 v[192:193], v[24:25], 0, s[20:21]
	global_load_dword v164, v[192:193], off
	v_lshl_add_u64 v[194:195], v[22:23], 0, s[20:21]
	global_load_dword v165, v[194:195], off
	v_lshl_add_u64 v[196:197], v[20:21], 0, s[20:21]
	global_load_dword v166, v[196:197], off
	v_lshl_add_u64 v[198:199], v[16:17], 0, s[20:21]
	global_load_dword v167, v[198:199], off
	s_add_u32 s20, s20, 0x30000
	s_addc_u32 s21, s21, 0
	v_lshl_add_u64 v[96:97], v[32:33], 0, s[20:21]
	global_load_dword v168, v[96:97], off
	v_lshl_add_u64 v[98:99], v[30:31], 0, s[20:21]
	global_load_dword v169, v[98:99], off
	v_lshl_add_u64 v[100:101], v[28:29], 0, s[20:21]
	global_load_dword v170, v[100:101], off
	v_lshl_add_u64 v[102:103], v[26:27], 0, s[20:21]
	global_load_dword v171, v[102:103], off
	v_lshl_add_u64 v[104:105], v[24:25], 0, s[20:21]
	global_load_dword v172, v[104:105], off
	v_lshl_add_u64 v[106:107], v[22:23], 0, s[20:21]
	global_load_dword v173, v[106:107], off
	v_lshl_add_u64 v[108:109], v[20:21], 0, s[20:21]
	global_load_dword v174, v[108:109], off
	v_lshl_add_u64 v[110:111], v[16:17], 0, s[20:21]
	global_load_dword v175, v[110:111], off
	s_add_u32 s20, s20, 0x30000
	s_addc_u32 s21, s21, 0
	s_waitcnt vmcnt(30)
	v_lshl_add_u64 v[184:185], v[32:33], 0, s[20:21]
	global_load_dword v176, v[184:185], off
	v_lshl_add_u64 v[186:187], v[30:31], 0, s[20:21]
	global_load_dword v177, v[186:187], off
	v_lshl_add_u64 v[188:189], v[28:29], 0, s[20:21]
	global_load_dword v178, v[188:189], off
	v_lshl_add_u64 v[190:191], v[26:27], 0, s[20:21]
	global_load_dword v179, v[190:191], off
	v_lshl_add_u64 v[192:193], v[24:25], 0, s[20:21]
	global_load_dword v180, v[192:193], off
	v_lshl_add_u64 v[194:195], v[22:23], 0, s[20:21]
	global_load_dword v181, v[194:195], off
	v_lshl_add_u64 v[196:197], v[20:21], 0, s[20:21]
	global_load_dword v182, v[196:197], off
	v_lshl_add_u64 v[198:199], v[16:17], 0, s[20:21]
	global_load_dword v183, v[198:199], off
	s_add_u32 s20, s20, 0x30000
	s_addc_u32 s21, s21, 0
	s_waitcnt vmcnt(24)
	v_mul_f32_e32 v152, v120, v152
	v_mul_f32_e32 v153, v121, v153
	v_mul_f32_e32 v154, v122, v154
	v_mul_f32_e32 v155, v123, v155
	v_mul_f32_e32 v156, v124, v156
	v_mul_f32_e32 v157, v125, v157
	v_mul_f32_e32 v158, v126, v158
	v_mul_f32_e32 v159, v127, v159
	ds_write_b32 v0, v152
	ds_write_b32 v0, v153 offset:264
	ds_write_b32 v0, v154 offset:528
	ds_write_b32 v0, v155 offset:792
	ds_write_b32 v0, v156 offset:1056
	ds_write_b32 v0, v157 offset:1320
	ds_write_b32 v0, v158 offset:1584
	ds_write_b32 v0, v159 offset:1848
	s_waitcnt vmcnt(16)
	v_mul_f32_e32 v160, v128, v160
	v_mul_f32_e32 v161, v129, v161
	v_mul_f32_e32 v162, v130, v162
	v_mul_f32_e32 v163, v131, v163
	v_mul_f32_e32 v164, v132, v164
	v_mul_f32_e32 v165, v133, v165
	v_mul_f32_e32 v166, v134, v166
	v_mul_f32_e32 v167, v135, v167
	ds_write_b32 v0, v160 offset:2112
	ds_write_b32 v0, v161 offset:2376
	ds_write_b32 v0, v162 offset:2640
	ds_write_b32 v0, v163 offset:2904
	ds_write_b32 v0, v164 offset:3168
	ds_write_b32 v0, v165 offset:3432
	ds_write_b32 v0, v166 offset:3696
	ds_write_b32 v0, v167 offset:3960
	s_waitcnt vmcnt(8)
	v_mul_f32_e32 v168, v136, v168
	v_mul_f32_e32 v169, v137, v169
	v_mul_f32_e32 v170, v138, v170
	v_mul_f32_e32 v171, v139, v171
	v_mul_f32_e32 v172, v140, v172
	v_mul_f32_e32 v173, v141, v173
	v_mul_f32_e32 v174, v142, v174
	v_mul_f32_e32 v175, v143, v175
	ds_write_b32 v0, v168 offset:4224
	ds_write_b32 v0, v169 offset:4488
	ds_write_b32 v0, v170 offset:4752
	ds_write_b32 v0, v171 offset:5016
	ds_write_b32 v0, v172 offset:5280
	ds_write_b32 v0, v173 offset:5544
	ds_write_b32 v0, v174 offset:5808
	ds_write_b32 v0, v175 offset:6072
	s_waitcnt vmcnt(0)
	v_mul_f32_e32 v176, v144, v176
	v_mul_f32_e32 v177, v145, v177
	v_mul_f32_e32 v178, v146, v178
	v_mul_f32_e32 v179, v147, v179
	v_mul_f32_e32 v180, v148, v180
	v_mul_f32_e32 v181, v149, v181
	v_mul_f32_e32 v182, v150, v182
	v_mul_f32_e32 v183, v151, v183
	ds_write_b32 v0, v176 offset:6336
	ds_write_b32 v0, v177 offset:6600
	ds_write_b32 v0, v178 offset:6864
	ds_write_b32 v0, v179 offset:7128
	ds_write_b32 v0, v180 offset:7392
	ds_write_b32 v0, v181 offset:7656
	ds_write_b32 v0, v182 offset:7920
	ds_write_b32 v0, v183 offset:8184
	s_add_u32 s8, s8, 0x100
	s_addc_u32 s9, s9, 0
	v_add_u32_e32 v0, 0x2100, v0
	s_branch .LBB0_605
